# P6 loop: QK rings wait once per MFMA pair, compiler leftover vmcnt waits removed from the common path (21 fewer wait instructions per iteration)
# speedup vs baseline: 1.0036x; 1.0036x over previous
; template <int KB, bool SK>
; __device__ __forceinline__ void qkt(f32x16& p0, f32x16& p1, const char* K_lds, int r32, int hi, const bf16x8* qr, bool act) {
;     if (SK && !act) return;
;     p0 = f32x16{}; p1 = f32x16{};
;     const char* kb[4];
; #pragma unroll
;     for (int dd = 0; dd < 4; ++dd) kb[dd] = K_lds + KB * SHM_K + KSWZ(r32, (dd * 16 + hi * 8) * 2);
; #pragma unroll
;     for (int d0 = 0; d0 < 8; ++d0) { const char* a = kb[d0 & 3] + (d0 >> 2) * 128;
;         bf16x8 b0 = *reinterpret_cast<const bf16x8*>(a);
;         bf16x8 b1 = *reinterpret_cast<const bf16x8*>(a + 32 * 256);
;         p0 = __builtin_amdgcn_mfma_f32_32x32x16_bf16(b0, qr[d0], p0, 0, 0, 0);
;         p1 = __builtin_amdgcn_mfma_f32_32x32x16_bf16(b1, qr[d0], p1, 0, 0, 0); }
; }
.LBB0_1332:
	s_andn2_b64 s[4:5], exec, s[82:83]
	s_andn2_b64 vcc, exec, s[82:83]
	s_cbranch_vccnz .LBB0_1334
	ds_read_b128 v[2:5], v239 offset:49152
	ds_read_b128 v[6:9], v239 offset:57344
	ds_read_b128 v[10:13], v240 offset:49152
	ds_read_b128 v[144:147], v240 offset:57344
	ds_read_b128 v[148:151], v241 offset:49152
	ds_read_b128 v[152:155], v241 offset:57344
	s_waitcnt lgkmcnt(4)
	v_mfma_f32_32x32x16_bf16 v[112:127], v[2:5], v[188:191], 0
	ds_read_b128 v[2:5], v242 offset:49152
	v_mfma_f32_32x32x16_bf16 v[80:95], v[6:9], v[188:191], 0
	ds_read_b128 v[6:9], v242 offset:57344
	s_waitcnt lgkmcnt(4)
	v_mfma_f32_32x32x16_bf16 v[112:127], v[10:13], v[184:187], v[112:127]
	ds_read_b128 v[10:13], v239 offset:49280
	v_mfma_f32_32x32x16_bf16 v[80:95], v[144:147], v[184:187], v[80:95]
	ds_read_b128 v[144:147], v239 offset:57472
	s_waitcnt lgkmcnt(4)
	v_mfma_f32_32x32x16_bf16 v[112:127], v[148:151], v[180:183], v[112:127]
	ds_read_b128 v[148:151], v240 offset:49280
	v_mfma_f32_32x32x16_bf16 v[80:95], v[152:155], v[180:183], v[80:95]
	ds_read_b128 v[152:155], v240 offset:57472
	s_waitcnt lgkmcnt(4)
	v_mfma_f32_32x32x16_bf16 v[112:127], v[2:5], v[176:179], v[112:127]
	ds_read_b128 v[2:5], v241 offset:49280
	v_mfma_f32_32x32x16_bf16 v[80:95], v[6:9], v[176:179], v[80:95]
	ds_read_b128 v[6:9], v241 offset:57472
	s_waitcnt lgkmcnt(4)
	v_mfma_f32_32x32x16_bf16 v[112:127], v[10:13], v[172:175], v[112:127]
	ds_read_b128 v[10:13], v242 offset:49280
	v_mfma_f32_32x32x16_bf16 v[80:95], v[144:147], v[172:175], v[80:95]
	ds_read_b128 v[144:147], v242 offset:57472
	s_waitcnt lgkmcnt(4)
	v_mfma_f32_32x32x16_bf16 v[112:127], v[148:151], v[168:171], v[112:127]
	v_mfma_f32_32x32x16_bf16 v[80:95], v[152:155], v[168:171], v[80:95]
	s_waitcnt lgkmcnt(2)
	v_mfma_f32_32x32x16_bf16 v[112:127], v[2:5], v[164:167], v[112:127]
	v_mfma_f32_32x32x16_bf16 v[80:95], v[6:9], v[164:167], v[80:95]
	s_waitcnt lgkmcnt(0)
	v_mfma_f32_32x32x16_bf16 v[112:127], v[10:13], v[160:163], v[112:127]
	v_mfma_f32_32x32x16_bf16 v[80:95], v[144:147], v[160:163], v[80:95]

; template <int VB, bool SK>
; __device__ __forceinline__ void pv_tile(f32x16* o, int vb0, bf16x8 pa0, bf16x8 pa1, bf16x8 pa2, bf16x8 pa3, bool act) {
;     if (SK && !act) return;
;     ...
;     PV_D0(0); PV_D0(1); PV_D0(2); PV_D0(3);
.LBB0_1336:
	s_mov_b32 s20, 0x1000000
	global_load_dwordx4 v[10:13], v248, s[98:99]
	global_load_dwordx4 v[208:211], v249, s[98:99]
	global_load_dwordx4 v[2:5], v248, s[100:101]
	global_load_dwordx4 v[6:9], v249, s[100:101]
	s_add_u32 s98, s98, 0x4000
	s_addc_u32 s99, s99, 0
	s_add_u32 s100, s100, 0x4000
	s_addc_u32 s101, s101, 0
	s_and_b64 vcc, exec, s[6:7]
	s_cbranch_vccnz .LBB0_1338
	ds_read_b64_tr_b16 v[144:145], v226 offset:0
	ds_read_b64_tr_b16 v[146:147], v226 offset:0x800
	ds_read_b64_tr_b16 v[148:149], v226 offset:0x1000
	ds_read_b64_tr_b16 v[150:151], v226 offset:0x1800
	ds_read_b64_tr_b16 v[152:153], v226 offset:0x2000
	ds_read_b64_tr_b16 v[154:155], v226 offset:0x2800
	ds_read_b64_tr_b16 v[156:157], v226 offset:0x3000
	ds_read_b64_tr_b16 v[158:159], v226 offset:0x3800
	s_waitcnt lgkmcnt(0)
	v_mfma_f32_32x32x16_bf16 v[64:79], v[192:195], v[144:147], v[64:79]
	ds_read_b64_tr_b16 v[144:145], v226 offset:0x200
	ds_read_b64_tr_b16 v[146:147], v226 offset:0xa00
	v_mfma_f32_32x32x16_bf16 v[64:79], v[196:199], v[148:151], v[64:79]
	ds_read_b64_tr_b16 v[148:149], v226 offset:0x1200
	ds_read_b64_tr_b16 v[150:151], v226 offset:0x1a00
	v_mfma_f32_32x32x16_bf16 v[64:79], v[200:203], v[152:155], v[64:79]
	ds_read_b64_tr_b16 v[152:153], v226 offset:0x2200
	ds_read_b64_tr_b16 v[154:155], v226 offset:0x2a00
	v_mfma_f32_32x32x16_bf16 v[64:79], v[204:207], v[156:159], v[64:79]
	ds_read_b64_tr_b16 v[156:157], v226 offset:0x3200
	ds_read_b64_tr_b16 v[158:159], v226 offset:0x3a00
	s_waitcnt lgkmcnt(0)
	v_mfma_f32_32x32x16_bf16 v[48:63], v[192:195], v[144:147], v[48:63]
	ds_read_b64_tr_b16 v[144:145], v226 offset:0x400
	ds_read_b64_tr_b16 v[146:147], v226 offset:0xc00
	v_mfma_f32_32x32x16_bf16 v[48:63], v[196:199], v[148:151], v[48:63]
	ds_read_b64_tr_b16 v[148:149], v226 offset:0x1400
	ds_read_b64_tr_b16 v[150:151], v226 offset:0x1c00
	v_mfma_f32_32x32x16_bf16 v[48:63], v[200:203], v[152:155], v[48:63]
	ds_read_b64_tr_b16 v[152:153], v226 offset:0x2400
	ds_read_b64_tr_b16 v[154:155], v226 offset:0x2c00
	v_mfma_f32_32x32x16_bf16 v[48:63], v[204:207], v[156:159], v[48:63]
	ds_read_b64_tr_b16 v[156:157], v226 offset:0x3400
	ds_read_b64_tr_b16 v[158:159], v226 offset:0x3c00
	s_waitcnt lgkmcnt(0)
	v_mfma_f32_32x32x16_bf16 v[32:47], v[192:195], v[144:147], v[32:47]
	ds_read_b64_tr_b16 v[144:145], v226 offset:0x600
	ds_read_b64_tr_b16 v[146:147], v226 offset:0xe00
	v_mfma_f32_32x32x16_bf16 v[32:47], v[196:199], v[148:151], v[32:47]
	ds_read_b64_tr_b16 v[148:149], v226 offset:0x1600
	ds_read_b64_tr_b16 v[150:151], v226 offset:0x1e00
	v_mfma_f32_32x32x16_bf16 v[32:47], v[200:203], v[152:155], v[32:47]
	ds_read_b64_tr_b16 v[152:153], v226 offset:0x2600
	ds_read_b64_tr_b16 v[154:155], v226 offset:0x2e00
	v_mfma_f32_32x32x16_bf16 v[32:47], v[204:207], v[156:159], v[32:47]
	ds_read_b64_tr_b16 v[156:157], v226 offset:0x3600
	ds_read_b64_tr_b16 v[158:159], v226 offset:0x3e00
	s_waitcnt lgkmcnt(0)
	v_mfma_f32_32x32x16_bf16 v[16:31], v[192:195], v[144:147], v[16:31]
	v_mfma_f32_32x32x16_bf16 v[16:31], v[196:199], v[148:151], v[16:31]
	v_mfma_f32_32x32x16_bf16 v[16:31], v[200:203], v[152:155], v[16:31]
	v_mfma_f32_32x32x16_bf16 v[16:31], v[204:207], v[156:159], v[16:31]

; template <int KB, bool SK>
; __device__ __forceinline__ void qkt(f32x16& p0, f32x16& p1, const char* K_lds, int r32, int hi, const bf16x8* qr, bool act) {
;     if (SK && !act) return;
;     p0 = f32x16{}; p1 = f32x16{};
;     const char* kb[4];
; #pragma unroll
;     for (int dd = 0; dd < 4; ++dd) kb[dd] = K_lds + KB * SHM_K + KSWZ(r32, (dd * 16 + hi * 8) * 2);
; #pragma unroll
;     for (int d0 = 0; d0 < 8; ++d0) { const char* a = kb[d0 & 3] + (d0 >> 2) * 128;
;         bf16x8 b0 = *reinterpret_cast<const bf16x8*>(a);
;         bf16x8 b1 = *reinterpret_cast<const bf16x8*>(a + 32 * 256);
;         p0 = __builtin_amdgcn_mfma_f32_32x32x16_bf16(b0, qr[d0], p0, 0, 0, 0);
;         p1 = __builtin_amdgcn_mfma_f32_32x32x16_bf16(b1, qr[d0], p1, 0, 0, 0); }
; }
.LBB0_1382:
	s_andn2_b64 s[6:7], exec, s[84:85]
	s_andn2_b64 vcc, exec, s[84:85]
	s_cbranch_vccnz .LBB0_1384
	ds_read_b128 v[144:147], v239 offset:32768
	ds_read_b128 v[148:151], v239 offset:40960
	ds_read_b128 v[152:155], v240 offset:32768
	ds_read_b128 v[156:159], v240 offset:40960
	ds_read_b128 v[244:247], v241 offset:32768
	ds_read_b128 v[252:255], v241 offset:40960
	s_waitcnt lgkmcnt(4)
	v_mfma_f32_32x32x16_bf16 v[128:143], v[144:147], v[188:191], 0
	ds_read_b128 v[144:147], v242 offset:32768
	v_mfma_f32_32x32x16_bf16 v[96:111], v[148:151], v[188:191], 0
	ds_read_b128 v[148:151], v242 offset:40960
	s_waitcnt lgkmcnt(4)
	v_mfma_f32_32x32x16_bf16 v[128:143], v[152:155], v[184:187], v[128:143]
	ds_read_b128 v[152:155], v239 offset:32896
	v_mfma_f32_32x32x16_bf16 v[96:111], v[156:159], v[184:187], v[96:111]
	ds_read_b128 v[156:159], v239 offset:41088
	s_waitcnt lgkmcnt(4)
	v_mfma_f32_32x32x16_bf16 v[128:143], v[244:247], v[180:183], v[128:143]
	ds_read_b128 v[244:247], v240 offset:32896
	v_mfma_f32_32x32x16_bf16 v[96:111], v[252:255], v[180:183], v[96:111]
	ds_read_b128 v[252:255], v240 offset:41088
	s_waitcnt lgkmcnt(4)
	v_mfma_f32_32x32x16_bf16 v[128:143], v[144:147], v[176:179], v[128:143]
	ds_read_b128 v[144:147], v241 offset:32896
	v_mfma_f32_32x32x16_bf16 v[96:111], v[148:151], v[176:179], v[96:111]
	ds_read_b128 v[148:151], v241 offset:41088
	s_waitcnt lgkmcnt(4)
	v_mfma_f32_32x32x16_bf16 v[128:143], v[152:155], v[172:175], v[128:143]
	ds_read_b128 v[152:155], v242 offset:32896
	v_mfma_f32_32x32x16_bf16 v[96:111], v[156:159], v[172:175], v[96:111]
	ds_read_b128 v[156:159], v242 offset:41088
	s_waitcnt lgkmcnt(4)
	v_mfma_f32_32x32x16_bf16 v[128:143], v[244:247], v[168:171], v[128:143]
	v_mfma_f32_32x32x16_bf16 v[96:111], v[252:255], v[168:171], v[96:111]
	s_waitcnt lgkmcnt(2)
	v_mfma_f32_32x32x16_bf16 v[128:143], v[144:147], v[164:167], v[128:143]
	v_mfma_f32_32x32x16_bf16 v[96:111], v[148:151], v[164:167], v[96:111]
	s_waitcnt lgkmcnt(0)
	v_mfma_f32_32x32x16_bf16 v[128:143], v[152:155], v[160:163], v[128:143]
	v_mfma_f32_32x32x16_bf16 v[96:111], v[156:159], v[160:163], v[96:111]
